# v14 + grid barrier: non-leader WGs poll the global generation word directly instead of waiting for their XCD leader to relay it
# speedup vs baseline: 1.0126x; 1.0126x over previous
; __device__ __forceinline__ unsigned xb_ld(unsigned* p)              { return __hip_atomic_load(p, __ATOMIC_RELAXED, __HIP_MEMORY_SCOPE_AGENT); }
; __device__ __forceinline__ unsigned xb_add(unsigned* p, unsigned v) { return __hip_atomic_fetch_add(p, v, __ATOMIC_RELAXED, __HIP_MEMORY_SCOPE_AGENT); }
; #define XB_SPIN(cond, bar) do { unsigned _sp = 0; while (cond) { __builtin_amdgcn_s_sleep(1); \
;     if ((++_sp & 255u) == 0u) { if (xb_ld(&(bar)[XB_TMO])) break; if (_sp > XB_SPIN_CAP) { atomicAdd(&(bar)[XB_TMO], 1u); break; } } } } while (0)
; __device__ __forceinline__ void xcd_barrier(const XcdBarrier& b) {
;     ...
;         const unsigned old = xb_add(&bar[XB_XSUB(b.x)], 1u);
;         const unsigned gen = old / nloc;
;         if (old + 1u == (gen + 1u) * nloc) {
;             __builtin_amdgcn_fence(__ATOMIC_RELEASE, "agent");
;             asm volatile("s_waitcnt vmcnt(0)" ::: "memory");
;             const unsigned og = xb_add(&bar[XB_TOP], 1u);
;             const unsigned tg = og / nx;
;             if (og + 1u == (tg + 1u) * nx) xb_add(&bar[XB_TOPGEN], 1u);
;             else XB_SPIN(xb_ld(&bar[XB_TOPGEN]) == tg, bar);
;             __builtin_amdgcn_fence(__ATOMIC_ACQUIRE, "agent");
;             xb_add(&bar[XB_XGEN(b.x)], 1u);
;             asm volatile("s_waitcnt vmcnt(0)" ::: "memory");
;         } else {
;             XB_SPIN(xb_ld(&bar[XB_XGEN(b.x)]) == gen, bar);
.LBB0_1125:
	s_or_b64 exec, exec, s[2:3]
	v_cvt_f32_u32_e32 v4, v2
	s_waitcnt vmcnt(0)
	v_readfirstlane_b32 s2, v3
	v_sub_u32_e32 v3, 0, v2
	v_rcp_iflag_f32_e32 v4, v4
	v_add_u32_e32 v5, s2, v1
	v_mul_f32_e32 v4, 0x4f7ffffe, v4
	v_cvt_u32_f32_e32 v4, v4
	v_mul_lo_u32 v1, v3, v4
	v_mul_hi_u32 v1, v4, v1
	v_add_u32_e32 v1, v4, v1
	v_mul_hi_u32 v1, v5, v1
	v_mul_lo_u32 v3, v1, v2
	v_sub_u32_e32 v3, v5, v3
	v_add_u32_e32 v4, 1, v1
	v_cmp_ge_u32_e32 vcc, v3, v2
	s_nop 1
	v_cndmask_b32_e32 v1, v1, v4, vcc
	v_sub_u32_e32 v4, v3, v2
	v_cndmask_b32_e32 v3, v3, v4, vcc
	v_add_u32_e32 v4, 1, v1
	v_cmp_ge_u32_e32 vcc, v3, v2
	v_add_u32_e32 v3, 1, v5
	s_nop 0
	v_cndmask_b32_e32 v1, v1, v4, vcc
	v_mul_lo_u32 v4, v2, v1
	v_add_u32_e32 v2, v4, v2
	v_cmp_ne_u32_e32 vcc, v3, v2
	s_and_saveexec_b64 s[2:3], vcc
	s_xor_b64 s[2:3], exec, s[2:3]
	s_cbranch_execz .LBB0_1139
	v_readlane_b32 s4, v253, 35
	v_readlane_b32 s5, v253, 36
	s_waitcnt lgkmcnt(0)
	s_nop 3
	global_load_dword v0, v185, s[4:5] sc1
	s_waitcnt vmcnt(0)
	v_cmp_eq_u32_e32 vcc, v0, v1
	s_and_saveexec_b64 s[6:7], vcc
	s_cbranch_execz .LBB0_1138
	s_mov_b32 s16, 1
	s_mov_b64 s[8:9], 0
	s_branch .LBB0_1129

; __device__ __forceinline__ unsigned xb_ld(unsigned* p)              { return __hip_atomic_load(p, __ATOMIC_RELAXED, __HIP_MEMORY_SCOPE_AGENT); }
; #define XB_SPIN(cond, bar) do { unsigned _sp = 0; while (cond) { __builtin_amdgcn_s_sleep(1); \
;     if ((++_sp & 255u) == 0u) { if (xb_ld(&(bar)[XB_TMO])) break; if (_sp > XB_SPIN_CAP) { atomicAdd(&(bar)[XB_TMO], 1u); break; } } } } while (0)
; __device__ __forceinline__ void xcd_barrier(const XcdBarrier& b) {
;     ...
;             XB_SPIN(xb_ld(&bar[XB_XGEN(b.x)]) == gen, bar);
.LBB0_1131:
	v_readlane_b32 s4, v253, 35
	v_readlane_b32 s5, v253, 36
	s_add_i32 s16, s16, 1
	s_mov_b64 s[14:15], -1
	s_nop 2
	global_load_dword v0, v185, s[4:5] sc1
	s_waitcnt vmcnt(0)
	v_cmp_ne_u32_e32 vcc, v0, v1
	s_orn2_b64 s[12:13], vcc, exec
	s_branch .LBB0_1128
